# grid barrier: the XCD leader's post-release L1 invalidate removed as well (every workgroup already invalidates right after its arrival atomic and issues no cached load until the closing barrier)
# baseline (speedup 1.0000x reference)
.LBB0_136:
	s_or_b64 exec, exec, s[2:3]
	s_mov_b64 s[2:3], exec
	v_mbcnt_lo_u32_b32 v0, s2, 0
	v_mbcnt_hi_u32_b32 v0, s3, v0
	v_cmp_eq_u32_e32 vcc, 0, v0
	s_waitcnt vmcnt(0)
	s_and_saveexec_b64 s[6:7], vcc
	s_cbranch_execz .LBB0_138
	s_bcnt1_i32_b64 s2, s[2:3]
	v_mov_b32_e32 v0, s2
	v_mov_b32_e32 v1, 0x2000
	global_atomic_add v1, v0, s[4:5] offset:1024

.LBB0_198:
	s_or_b64 exec, exec, s[6:7]
	s_mov_b64 s[6:7], exec
	v_mbcnt_lo_u32_b32 v0, s6, 0
	v_mbcnt_hi_u32_b32 v0, s7, v0
	v_cmp_eq_u32_e32 vcc, 0, v0
	s_waitcnt vmcnt(0)
	s_and_saveexec_b64 s[12:13], vcc
	s_cbranch_execz .LBB0_200
	s_bcnt1_i32_b64 s6, s[6:7]
	v_mov_b32_e32 v0, s6
	v_mov_b32_e32 v1, 0x2000
	global_atomic_add v1, v0, s[10:11] offset:1024

.LBB0_257:
	s_or_b64 exec, exec, s[4:5]
	s_mov_b64 s[4:5], exec
	v_mbcnt_lo_u32_b32 v0, s4, 0
	v_mbcnt_hi_u32_b32 v0, s5, v0
	v_cmp_eq_u32_e32 vcc, 0, v0
	s_waitcnt vmcnt(0)
	s_and_saveexec_b64 s[10:11], vcc
	s_cbranch_execz .LBB0_259
	s_bcnt1_i32_b64 s4, s[4:5]
	v_mov_b32_e32 v0, s4
	v_mov_b32_e32 v1, 0x2000
	global_atomic_add v1, v0, s[6:7] offset:1024

.LBB0_1024:
	s_or_b64 exec, exec, s[2:3]
	s_mov_b64 s[2:3], exec
	v_mbcnt_lo_u32_b32 v0, s2, 0
	v_mbcnt_hi_u32_b32 v0, s3, v0
	v_cmp_eq_u32_e32 vcc, 0, v0
	s_waitcnt vmcnt(0)
	s_and_saveexec_b64 s[18:19], vcc
	s_cbranch_execz .LBB0_1026
	s_bcnt1_i32_b64 s2, s[2:3]
	v_mov_b32_e32 v0, s2
	v_mov_b32_e32 v1, 0x2000
	global_atomic_add v1, v0, s[16:17] offset:1024

.LBB0_2482:
	s_or_b64 exec, exec, s[2:3]
	s_mov_b64 s[2:3], exec
	v_mbcnt_lo_u32_b32 v0, s2, 0
	v_mbcnt_hi_u32_b32 v0, s3, v0
	v_cmp_eq_u32_e32 vcc, 0, v0
	s_waitcnt vmcnt(0)
	s_and_saveexec_b64 s[8:9], vcc
	s_cbranch_execz .LBB0_2484
	s_bcnt1_i32_b64 s2, s[2:3]
	v_mov_b32_e32 v0, s2
	v_mov_b32_e32 v1, 0x2000
	global_atomic_add v1, v0, s[6:7] offset:1024

.LBB0_2602:
	s_or_b64 exec, exec, s[2:3]
	s_mov_b64 s[2:3], exec
	v_mbcnt_lo_u32_b32 v0, s2, 0
	v_mbcnt_hi_u32_b32 v0, s3, v0
	v_cmp_eq_u32_e32 vcc, 0, v0
	s_waitcnt vmcnt(0)
	s_and_saveexec_b64 s[6:7], vcc
	s_cbranch_execnz .LBB0_2603
	s_getpc_b64 s[98:99]
